# EpiMla epilogue: pairs of 8-byte stores merged into 16-byte stores, rope address hoisted
# speedup vs baseline: 1.0816x; 1.0041x over previous
; #define PIN(i) ((const float*)(const GASP float*)karg_q(i))
;     __device__ __forceinline__ void operator()(const f32x4 (&acc)[2][2][4][2], const Unit& u, int wr, int wc, int, int) const {
;         const int lane_ = ::otid() & 63, fr = lane_ & 15, fq = lane_ >> 4;
;         unsigned char* ws = PWS;
;         const bool isq = u.pn < 3; const int head = (isq ? u.pn : u.pn - 3) * 2 + (wc >> 1), kind = wc & 1;
;         const bool latent = u.pm < 128, is_v = !isq && kind == 1, is_rope = isq && kind == 1, rot = is_rope && latent;
;         const int sbj = is_rope ? 8 : 32;
;         const float* gsrc = is_v ? (const float*)(ws + WS_ROPE) + 1024 : (isq ? PIN(16) + l * 96 : PIN(17) + l * 96);
;         const float* g = gsrc + (is_rope ? 64 + 16 * (fq & 1) : 8 * fq);
;         const float* rope = (const float*)(ws + WS_ROPE);
;         bf16_t* obase = (bf16_t*)(ws + (is_v ? WS_MV : (isq ? WS_MQ : WS_MK)));
;         const int ostride = is_v ? 384 : 576;
;         const int ocol = is_v ? head * 64 + 8 * fq : head * 96 + (is_rope ? 64 + 16 * (fq & 1) : 8 * fq);
;         const float inv_cnt = is_rope ? (1.0f / 32.0f) : (1.0f / 64.0f), sc = isq ? MLA_SCALE : 1.0f;
;         const bool st_ok = !is_rope || fq < 2;
;         const int rowb = u.pm * BM + wr * 64 + fr;
; #pragma unroll
;         for (int ai = 0; ai < 2; ++ai)
; #pragma unroll
;             for (int m = 0; m < 4; ++m) {
;                 const int row = rowb + ai * HALF + m * 16;
;                 float ss = 0.f;
; #pragma unroll
;                 for (int j = 0; j < 4; ++j) ss += acc[ai][0][m][0][j] * acc[ai][0][m][0][j] + acc[ai][0][m][1][j] * acc[ai][0][m][1][j] + acc[ai][1][m][0][j] * acc[ai][1][m][0][j] + acc[ai][1][m][1][j] * acc[ai][1][m][1][j];
;                 ss += ::swz<16>(ss); ss = ::x32_sum(ss);
;                 float rs = rsqrtf(ss * inv_cnt + 1e-6f) * sc; rs = is_v ? 1.0f : rs;
;                 const int pos = row & 2047, pp = rot ? ((fq & 1) ? (pos & 63) : (pos >> 6)) : 0;
;                 const float* rt = rope + pp * 16;
;                 bf16_t* dst = obase + (unsigned)(row * ostride + ocol);
; #pragma unroll
;                 for (int n = 0; n < 2; ++n) {
;                     const f32x4 g1 = *(const f32x4*)(g + 4 * n), g2 = *(const f32x4*)(g + sbj + 4 * n);
;                     const f32x4 t0 = *(const f32x4*)(rt + 8 * n), t1 = *(const f32x4*)(rt + 8 * n + 4);
.LBB0_669:
	v_and_b32_e32 v161, 15, v140
	v_mov_b32_e32 v140, 0x3c800000
	v_mov_b32_e32 v143, 0x3d000000
	v_lshlrev_b32_e32 v138, 2, v138
	v_mov_b32_e32 v139, v0
	v_cndmask_b32_e64 v159, v140, v143, s[42:43]
	v_mov_b32_e32 v140, 0x3e16c740
	v_lshl_add_u64 v[138:139], s[2:3], 0, v[138:139]
	global_load_dwordx4 v[172:175], v[138:139], off
	s_and_b64 s[2:3], s[40:41], exec
	v_cndmask_b32_e64 v143, 1.0, v140, s[40:41]
	v_cmp_gt_u32_e64 s[40:41], 2, v141
	v_mul_f32_e32 v140, v118, v118
	v_mul_f32_e32 v141, v119, v119
	v_fmac_f32_e32 v140, v126, v126
	v_fmac_f32_e32 v141, v127, v127
	v_fmac_f32_e32 v140, v122, v122
	v_fmac_f32_e32 v141, v123, v123
	v_fmac_f32_e32 v140, v114, v114
	v_fmac_f32_e32 v141, v115, v115
	v_add_f32_e32 v140, v140, v141
	v_mul_f32_e32 v141, v120, v120
	v_fmac_f32_e32 v141, v128, v128
	s_cselect_b32 s3, 0x16b98000, s76
	v_fmac_f32_e32 v141, v124, v124
	s_cselect_b32 s2, 0, 0
	s_add_u32 s60, s56, s3
	v_fmac_f32_e32 v141, v116, v116
	s_addc_u32 s61, s57, s2
	v_add_f32_e32 v140, v141, v140
	v_mul_f32_e32 v141, v121, v121
	s_cmpk_lt_i32 s54, 0x80
	v_fmac_f32_e32 v141, v129, v129
	s_cselect_b64 s[2:3], -1, 0
	v_fmac_f32_e32 v141, v125, v125
	s_and_b64 vcc, s[42:43], s[2:3]
	s_xor_b64 s[2:3], s[42:43], -1
	v_fmac_f32_e32 v141, v117, v117
	s_or_b64 s[20:21], s[2:3], s[40:41]
	v_cmp_eq_u32_e64 s[40:41], 0, v144
	v_add_f32_e32 v144, v141, v140
	ds_swizzle_b32 v145, v144 offset:swizzle(SWAP,16)
	s_lshl_b32 s2, s54, 8
	s_add_i32 s5, s2, s78
	s_and_b64 s[2:3], s[42:43], exec
	s_cselect_b32 s16, 8, 32
	s_waitcnt lgkmcnt(0)
	v_add_f32_e32 v158, v144, v145
	s_lshl_b32 s54, s16, 2
	v_mov_b32_e32 v162, v158
	v_or_b32_e32 v160, s5, v161
	v_lshl_add_u64 v[140:141], v[138:139], 0, s[54:55]
	s_bfe_u32 s17, s5, 0x50006
	v_mov_b32_e32 v248, s17
	v_cndmask_b32_e64 v248, v161, v248, s[40:41]
	v_lshlrev_b32_e32 v248, 4, v248
	v_cndmask_b32_e32 v248, 0, v248, vcc
	v_lshlrev_b32_e32 v249, 2, v248
	global_load_dwordx4 v[176:179], v249, s[22:23]
	global_load_dwordx4 v[180:183], v249, s[22:23] offset:16
	global_load_dwordx4 v[184:187], v[140:141], off
	global_load_dwordx4 v[188:191], v[138:139], off offset:16
	global_load_dwordx4 v[192:195], v249, s[22:23] offset:32
	global_load_dwordx4 v[196:199], v249, s[22:23] offset:48
	global_load_dwordx4 v[200:203], v[140:141], off offset:16
	v_permlane32_swap_b32_e32 v158, v162
	s_and_saveexec_b64 s[2:3], s[20:21]
	v_add_f32_e32 v146, v158, v162
	v_mad_u64_u32 v[144:145], s[42:43], s26, v160, v[142:143]
	v_fmaak_f32 v146, v159, v146, 0x358637bd
	v_cmp_gt_f32_e64 s[42:43], s88, v146
	v_mul_f32_e32 v147, 0x4b800000, v146
	v_mov_b32_e32 v145, v0
	v_cndmask_b32_e64 v146, v146, v147, s[42:43]
	v_rsq_f32_e32 v146, v146
	v_lshl_add_u64 v[156:157], v[144:145], 1, s[60:61]
	s_lshl_b32 s54, s16, 1
	v_lshl_add_u64 v[144:145], v[156:157], 0, s[54:55]
	v_mul_f32_e32 v147, 0x45800000, v146
	v_cndmask_b32_e64 v146, v146, v147, s[42:43]
	v_mul_f32_e32 v146, v143, v146
	v_cndmask_b32_e64 v158, v146, 1.0, s[50:51]
	v_pk_mul_f32 v[146:147], v[128:129], v[158:159] op_sel_hi:[1,0]
	v_pk_mul_f32 v[148:149], v[126:127], v[158:159] op_sel_hi:[1,0]
	global_load_dwordx4 v[204:207], v[138:139], off
	v_pk_mul_f32 v[150:151], v[122:123], v[158:159] op_sel_hi:[1,0]
	v_pk_mul_f32 v[152:153], v[124:125], v[158:159] op_sel_hi:[1,0]
	s_waitcnt vmcnt(8)
	v_pk_mul_f32 v[148:149], v[148:149], v[172:173]
	v_pk_mul_f32 v[146:147], v[146:147], v[174:175]
	s_waitcnt vmcnt(6)
	v_mov_b32_e32 v166, v180
	s_waitcnt vmcnt(5)
	v_pk_mul_f32 v[124:125], v[152:153], v[186:187]
	v_pk_mul_f32 v[122:123], v[150:151], v[184:185]
	v_mov_b32_e32 v150, v176
	v_mov_b32_e32 v151, v178
	v_mov_b32_e32 v167, v182
	v_mov_b32_e32 v182, v181
	v_mov_b32_e32 v178, v177
	v_pk_mul_f32 v[152:153], v[150:151], v[122:123]
	v_pk_mul_f32 v[168:169], v[166:167], v[124:125]
	v_pk_mul_f32 v[122:123], v[178:179], v[122:123]
	v_pk_mul_f32 v[124:125], v[182:183], v[124:125]
	v_pk_fma_f32 v[122:123], v[148:149], v[150:151], v[122:123] neg_lo:[0,0,1] neg_hi:[0,0,1]
	v_pk_fma_f32 v[124:125], v[146:147], v[166:167], v[124:125] neg_lo:[0,0,1] neg_hi:[0,0,1]
	v_pk_fma_f32 v[162:163], v[146:147], v[182:183], v[168:169]
	v_pk_fma_f32 v[126:127], v[148:149], v[178:179], v[152:153]
	v_cvt_pk_bf16_f32 v240, v122, v123
	v_cvt_pk_bf16_f32 v241, v124, v125
	v_cvt_pk_bf16_f32 v244, v126, v127
	v_cvt_pk_bf16_f32 v245, v162, v163
	v_pk_mul_f32 v[122:123], v[120:121], v[158:159] op_sel_hi:[1,0]
	v_pk_mul_f32 v[124:125], v[118:119], v[158:159] op_sel_hi:[1,0]
	v_pk_mul_f32 v[146:147], v[114:115], v[158:159] op_sel_hi:[1,0]
	v_pk_mul_f32 v[148:149], v[116:117], v[158:159] op_sel_hi:[1,0]
	s_waitcnt vmcnt(4)
	v_pk_mul_f32 v[126:127], v[124:125], v[188:189]
	v_pk_mul_f32 v[128:129], v[122:123], v[190:191]
	s_waitcnt vmcnt(2)
	v_mov_b32_e32 v150, v196
	s_waitcnt vmcnt(1)
	v_pk_mul_f32 v[116:117], v[148:149], v[202:203]
	v_pk_mul_f32 v[114:115], v[146:147], v[200:201]
	v_mov_b32_e32 v146, v192
	v_mov_b32_e32 v147, v194
	v_mov_b32_e32 v151, v198
	v_mov_b32_e32 v198, v197
	v_mov_b32_e32 v194, v193
	v_pk_mul_f32 v[148:149], v[146:147], v[114:115]
	v_pk_mul_f32 v[152:153], v[150:151], v[116:117]
	v_pk_mul_f32 v[114:115], v[194:195], v[114:115]
	v_pk_mul_f32 v[116:117], v[198:199], v[116:117]
	v_pk_fma_f32 v[114:115], v[126:127], v[146:147], v[114:115] neg_lo:[0,0,1] neg_hi:[0,0,1]
	v_pk_fma_f32 v[116:117], v[128:129], v[150:151], v[116:117] neg_lo:[0,0,1] neg_hi:[0,0,1]
	v_pk_fma_f32 v[122:123], v[128:129], v[198:199], v[152:153]
	v_pk_fma_f32 v[118:119], v[126:127], v[194:195], v[148:149]
	v_cvt_pk_bf16_f32 v242, v114, v115
	v_cvt_pk_bf16_f32 v243, v116, v117
	global_store_dwordx4 v[156:157], v[240:243], off
	v_cvt_pk_bf16_f32 v246, v118, v119
	v_cvt_pk_bf16_f32 v247, v122, v123
	global_store_dwordx4 v[144:145], v[244:247], off
; template <int K> __device__ __forceinline__ float swz(float v) { return __int_as_float(__builtin_amdgcn_ds_swizzle(__float_as_int(v), (K << 10) | 0x1f)); }
; __device__ __forceinline__ float x32_sum(float v) { auto r = __builtin_amdgcn_permlane32_swap(__float_as_uint(v), __float_as_uint(v), false, false); return __uint_as_float(r[0]) + __uint_as_float(r[1]); }
; __device__ __forceinline__ unsigned cvt_pk_bf16(float lo, float hi) { const f32x2c f = {lo, hi}; return __builtin_bit_cast(unsigned, __builtin_convertvector(f, bf16x2c)); }
;     __device__ __forceinline__ void operator()(const f32x4 (&acc)[2][2][4][2], const Unit& u, int wr, int wc, int, int) const {
;     ...
;             for (int m = 0; m < 4; ++m) {
;                 const int row = rowb + ai * HALF + m * 16;
;                 float ss = 0.f;
; #pragma unroll
;                 for (int j = 0; j < 4; ++j) ss += acc[ai][0][m][0][j] * acc[ai][0][m][0][j] + acc[ai][0][m][1][j] * acc[ai][0][m][1][j] + acc[ai][1][m][0][j] * acc[ai][1][m][0][j] + acc[ai][1][m][1][j] * acc[ai][1][m][1][j];
;                 ss += ::swz<16>(ss); ss = ::x32_sum(ss);
;                 float rs = rsqrtf(ss * inv_cnt + 1e-6f) * sc; rs = is_v ? 1.0f : rs;
;                 const int pos = row & 2047, pp = rot ? ((fq & 1) ? (pos & 63) : (pos >> 6)) : 0;
;                 const float* rt = rope + pp * 16;
;                 bf16_t* dst = obase + (unsigned)(row * ostride + ocol);
; #pragma unroll
;                 for (int n = 0; n < 2; ++n) {
;                     const f32x4 g1 = *(const f32x4*)(g + 4 * n), g2 = *(const f32x4*)(g + sbj + 4 * n);
;                     const f32x4 t0 = *(const f32x4*)(rt + 8 * n), t1 = *(const f32x4*)(rt + 8 * n + 4);
;                     const f32x4 c = (f32x4){t0[0], t0[2], t1[0], t1[2]}, s = (f32x4){t0[1], t0[3], t1[1], t1[3]};
;                     const f32x4 a1 = acc[ai][0][m][n] * rs * g1, a2 = acc[ai][1][m][n] * rs * g2;
;                     const f32x4 o1 = a1 * c - a2 * s, o2 = a1 * s + a2 * c;
;                     if (st_ok) { u32x2 w; w.x = cvt_pk_bf16(o1[0], o1[1]); w.y = cvt_pk_bf16(o1[2], o1[3]); *(u32x2*)(dst + 4 * n) = w;
;                         w.x = cvt_pk_bf16(o2[0], o2[1]); w.y = cvt_pk_bf16(o2[2], o2[3]); *(u32x2*)(dst + sbj + 4 * n) = w; }
;                 }
;                 asm volatile("" ::: "memory");
.LBB0_671:
	s_or_b64 exec, exec, s[2:3]
	v_mul_f32_e32 v114, v102, v102
	v_mul_f32_e32 v115, v103, v103
	v_fmac_f32_e32 v114, v110, v110
	v_fmac_f32_e32 v115, v111, v111
	v_fmac_f32_e32 v114, v106, v106
	v_fmac_f32_e32 v115, v107, v107
	v_fmac_f32_e32 v114, v98, v98
	v_fmac_f32_e32 v115, v99, v99
	v_add_f32_e32 v114, v114, v115
	v_mul_f32_e32 v115, v104, v104
	v_fmac_f32_e32 v115, v112, v112
	v_fmac_f32_e32 v115, v108, v108
	v_fmac_f32_e32 v115, v100, v100
	v_add_f32_e32 v114, v115, v114
	v_mul_f32_e32 v115, v105, v105
	v_fmac_f32_e32 v115, v113, v113
	v_fmac_f32_e32 v115, v109, v109
	v_fmac_f32_e32 v115, v101, v101
	v_add_f32_e32 v114, v115, v114
	ds_swizzle_b32 v115, v114 offset:swizzle(SWAP,16)
	v_or_b32_e32 v119, 16, v161
	v_mov_b32_e32 v250, s17
	v_cndmask_b32_e64 v250, v119, v250, s[40:41]
	v_lshlrev_b32_e32 v250, 4, v250
	v_cndmask_b32_e32 v250, 0, v250, vcc
	v_lshlrev_b32_e32 v251, 2, v250
	global_load_dwordx4 v[172:175], v251, s[22:23]
	global_load_dwordx4 v[176:179], v251, s[22:23] offset:16
	global_load_dwordx4 v[180:183], v[140:141], off
	global_load_dwordx4 v[184:187], v[138:139], off offset:16
	global_load_dwordx4 v[188:191], v251, s[22:23] offset:32
	global_load_dwordx4 v[192:195], v251, s[22:23] offset:48
	global_load_dwordx4 v[196:199], v[140:141], off offset:16
	s_waitcnt lgkmcnt(0)
	v_add_f32_e32 v118, v114, v115
	v_mov_b32_e32 v120, v118
	s_nop 1
	v_permlane32_swap_b32_e32 v118, v120
	s_and_saveexec_b64 s[2:3], s[20:21]
	v_or_b32_e32 v114, 16, v160
	v_add_f32_e32 v118, v118, v120
	v_mad_u64_u32 v[114:115], s[42:43], s26, v114, v[142:143]
	v_fmaak_f32 v118, v159, v118, 0x358637bd
	v_cmp_gt_f32_e64 s[42:43], s88, v118
	v_mul_f32_e32 v120, 0x4b800000, v118
	v_mov_b32_e32 v115, v0
	v_cndmask_b32_e64 v118, v118, v120, s[42:43]
	v_rsq_f32_e32 v118, v118
	v_lshl_add_u64 v[116:117], v[114:115], 1, s[60:61]
	s_lshl_b32 s54, s16, 1
	v_lshl_add_u64 v[114:115], v[116:117], 0, s[54:55]
	v_mul_f32_e32 v120, 0x45800000, v118
	v_cndmask_b32_e64 v118, v118, v120, s[42:43]
	v_mul_f32_e32 v118, v143, v118
	v_cndmask_b32_e64 v118, v118, 1.0, s[50:51]
	v_pk_mul_f32 v[120:121], v[112:113], v[118:119] op_sel_hi:[1,0]
	v_pk_mul_f32 v[122:123], v[110:111], v[118:119] op_sel_hi:[1,0]
	global_load_dwordx4 v[200:203], v[138:139], off
	v_pk_mul_f32 v[128:129], v[106:107], v[118:119] op_sel_hi:[1,0]
	v_pk_mul_f32 v[144:145], v[108:109], v[118:119] op_sel_hi:[1,0]
	s_waitcnt vmcnt(10)
	v_pk_mul_f32 v[124:125], v[122:123], v[204:205]
	v_pk_mul_f32 v[126:127], v[120:121], v[206:207]
	s_waitcnt vmcnt(6)
	v_mov_b32_e32 v146, v176
	s_waitcnt vmcnt(5)
	v_pk_mul_f32 v[108:109], v[144:145], v[182:183]
	v_pk_mul_f32 v[106:107], v[128:129], v[180:181]
	v_mov_b32_e32 v128, v172
	v_mov_b32_e32 v129, v174
	v_mov_b32_e32 v147, v178
	v_mov_b32_e32 v178, v177
	v_mov_b32_e32 v174, v173
	v_pk_mul_f32 v[144:145], v[128:129], v[106:107]
	v_pk_mul_f32 v[148:149], v[146:147], v[108:109]
	v_pk_mul_f32 v[106:107], v[174:175], v[106:107]
	v_pk_mul_f32 v[108:109], v[178:179], v[108:109]
	v_pk_fma_f32 v[106:107], v[124:125], v[128:129], v[106:107] neg_lo:[0,0,1] neg_hi:[0,0,1]
	v_pk_fma_f32 v[108:109], v[126:127], v[146:147], v[108:109] neg_lo:[0,0,1] neg_hi:[0,0,1]
	v_pk_fma_f32 v[120:121], v[126:127], v[178:179], v[148:149]
	v_pk_fma_f32 v[110:111], v[124:125], v[174:175], v[144:145]
	v_cvt_pk_bf16_f32 v240, v106, v107
	v_cvt_pk_bf16_f32 v241, v108, v109
	v_cvt_pk_bf16_f32 v244, v110, v111
	v_cvt_pk_bf16_f32 v245, v120, v121
	v_pk_mul_f32 v[106:107], v[104:105], v[118:119] op_sel_hi:[1,0]
	v_pk_mul_f32 v[108:109], v[102:103], v[118:119] op_sel_hi:[1,0]
	v_pk_mul_f32 v[120:121], v[98:99], v[118:119] op_sel_hi:[1,0]
	v_pk_mul_f32 v[122:123], v[100:101], v[118:119] op_sel_hi:[1,0]
	s_waitcnt vmcnt(4)
	v_pk_mul_f32 v[110:111], v[108:109], v[184:185]
	v_pk_mul_f32 v[112:113], v[106:107], v[186:187]
	s_waitcnt vmcnt(2)
	v_mov_b32_e32 v124, v192
	s_waitcnt vmcnt(1)
	v_pk_mul_f32 v[100:101], v[122:123], v[198:199]
	v_pk_mul_f32 v[98:99], v[120:121], v[196:197]
	v_mov_b32_e32 v120, v188
	v_mov_b32_e32 v121, v190
	v_mov_b32_e32 v125, v194
	v_mov_b32_e32 v194, v193
	v_mov_b32_e32 v190, v189
	v_pk_mul_f32 v[122:123], v[120:121], v[98:99]
	v_pk_mul_f32 v[126:127], v[124:125], v[100:101]
	v_pk_mul_f32 v[98:99], v[190:191], v[98:99]
	v_pk_mul_f32 v[100:101], v[194:195], v[100:101]
	v_pk_fma_f32 v[98:99], v[110:111], v[120:121], v[98:99] neg_lo:[0,0,1] neg_hi:[0,0,1]
	v_pk_fma_f32 v[100:101], v[112:113], v[124:125], v[100:101] neg_lo:[0,0,1] neg_hi:[0,0,1]
	v_pk_fma_f32 v[106:107], v[112:113], v[194:195], v[126:127]
	v_pk_fma_f32 v[102:103], v[110:111], v[190:191], v[122:123]
	v_cvt_pk_bf16_f32 v242, v98, v99
	v_cvt_pk_bf16_f32 v243, v100, v101
	global_store_dwordx4 v[116:117], v[240:243], off
	v_cvt_pk_bf16_f32 v246, v102, v103
	v_cvt_pk_bf16_f32 v247, v106, v107
	global_store_dwordx4 v[114:115], v[244:247], off
; template <int K> __device__ __forceinline__ float swz(float v) { return __int_as_float(__builtin_amdgcn_ds_swizzle(__float_as_int(v), (K << 10) | 0x1f)); }
; __device__ __forceinline__ float x32_sum(float v) { auto r = __builtin_amdgcn_permlane32_swap(__float_as_uint(v), __float_as_uint(v), false, false); return __uint_as_float(r[0]) + __uint_as_float(r[1]); }
; __device__ __forceinline__ unsigned cvt_pk_bf16(float lo, float hi) { const f32x2c f = {lo, hi}; return __builtin_bit_cast(unsigned, __builtin_convertvector(f, bf16x2c)); }
;     __device__ __forceinline__ void operator()(const f32x4 (&acc)[2][2][4][2], const Unit& u, int wr, int wc, int, int) const {
;     ...
;             for (int m = 0; m < 4; ++m) {
;                 const int row = rowb + ai * HALF + m * 16;
;                 float ss = 0.f;
; #pragma unroll
;                 for (int j = 0; j < 4; ++j) ss += acc[ai][0][m][0][j] * acc[ai][0][m][0][j] + acc[ai][0][m][1][j] * acc[ai][0][m][1][j] + acc[ai][1][m][0][j] * acc[ai][1][m][0][j] + acc[ai][1][m][1][j] * acc[ai][1][m][1][j];
;                 ss += ::swz<16>(ss); ss = ::x32_sum(ss);
;                 float rs = rsqrtf(ss * inv_cnt + 1e-6f) * sc; rs = is_v ? 1.0f : rs;
;                 const int pos = row & 2047, pp = rot ? ((fq & 1) ? (pos & 63) : (pos >> 6)) : 0;
;                 const float* rt = rope + pp * 16;
;                 bf16_t* dst = obase + (unsigned)(row * ostride + ocol);
; #pragma unroll
;                 for (int n = 0; n < 2; ++n) {
;                     const f32x4 g1 = *(const f32x4*)(g + 4 * n), g2 = *(const f32x4*)(g + sbj + 4 * n);
;                     const f32x4 t0 = *(const f32x4*)(rt + 8 * n), t1 = *(const f32x4*)(rt + 8 * n + 4);
;                     const f32x4 c = (f32x4){t0[0], t0[2], t1[0], t1[2]}, s = (f32x4){t0[1], t0[3], t1[1], t1[3]};
;                     const f32x4 a1 = acc[ai][0][m][n] * rs * g1, a2 = acc[ai][1][m][n] * rs * g2;
;                     const f32x4 o1 = a1 * c - a2 * s, o2 = a1 * s + a2 * c;
;                     if (st_ok) { u32x2 w; w.x = cvt_pk_bf16(o1[0], o1[1]); w.y = cvt_pk_bf16(o1[2], o1[3]); *(u32x2*)(dst + 4 * n) = w;
;                         w.x = cvt_pk_bf16(o2[0], o2[1]); w.y = cvt_pk_bf16(o2[2], o2[3]); *(u32x2*)(dst + sbj + 4 * n) = w; }
;                 }
;                 asm volatile("" ::: "memory");
.LBB0_673:
	s_or_b64 exec, exec, s[2:3]
	v_mul_f32_e32 v98, v86, v86
	v_mul_f32_e32 v99, v87, v87
	v_fmac_f32_e32 v98, v94, v94
	v_fmac_f32_e32 v99, v95, v95
	v_fmac_f32_e32 v98, v90, v90
	v_fmac_f32_e32 v99, v91, v91
	v_fmac_f32_e32 v98, v82, v82
	v_fmac_f32_e32 v99, v83, v83
	v_add_f32_e32 v98, v98, v99
	v_mul_f32_e32 v99, v88, v88
	v_fmac_f32_e32 v99, v96, v96
	v_fmac_f32_e32 v99, v92, v92
	v_fmac_f32_e32 v99, v84, v84
	v_add_f32_e32 v98, v99, v98
	v_mul_f32_e32 v99, v89, v89
	v_fmac_f32_e32 v99, v97, v97
	v_fmac_f32_e32 v99, v93, v93
	v_fmac_f32_e32 v99, v85, v85
	v_add_f32_e32 v98, v99, v98
	ds_swizzle_b32 v99, v98 offset:swizzle(SWAP,16)
	v_or_b32_e32 v103, 32, v161
	v_mov_b32_e32 v248, s17
	v_cndmask_b32_e64 v248, v103, v248, s[40:41]
	v_lshlrev_b32_e32 v248, 4, v248
	v_cndmask_b32_e32 v248, 0, v248, vcc
	v_lshlrev_b32_e32 v249, 2, v248
	global_load_dwordx4 v[172:175], v249, s[22:23]
	global_load_dwordx4 v[176:179], v249, s[22:23] offset:16
	global_load_dwordx4 v[180:183], v[140:141], off
	global_load_dwordx4 v[184:187], v[138:139], off offset:16
	global_load_dwordx4 v[188:191], v249, s[22:23] offset:32
	global_load_dwordx4 v[192:195], v249, s[22:23] offset:48
	global_load_dwordx4 v[196:199], v[140:141], off offset:16
	s_waitcnt lgkmcnt(0)
	v_add_f32_e32 v102, v98, v99
	v_mov_b32_e32 v104, v102
	s_nop 1
	v_permlane32_swap_b32_e32 v102, v104
	s_and_saveexec_b64 s[2:3], s[20:21]
	v_or_b32_e32 v98, 32, v160
	v_add_f32_e32 v102, v102, v104
	v_mad_u64_u32 v[98:99], s[42:43], s26, v98, v[142:143]
	v_fmaak_f32 v102, v159, v102, 0x358637bd
	v_cmp_gt_f32_e64 s[42:43], s88, v102
	v_mul_f32_e32 v104, 0x4b800000, v102
	v_mov_b32_e32 v99, v0
	v_cndmask_b32_e64 v102, v102, v104, s[42:43]
	v_rsq_f32_e32 v102, v102
	v_lshl_add_u64 v[100:101], v[98:99], 1, s[60:61]
	s_lshl_b32 s54, s16, 1
	v_lshl_add_u64 v[98:99], v[100:101], 0, s[54:55]
	v_mul_f32_e32 v104, 0x45800000, v102
	v_cndmask_b32_e64 v102, v102, v104, s[42:43]
	v_mul_f32_e32 v102, v143, v102
	v_cndmask_b32_e64 v102, v102, 1.0, s[50:51]
	v_pk_mul_f32 v[104:105], v[96:97], v[102:103] op_sel_hi:[1,0]
	v_pk_mul_f32 v[106:107], v[94:95], v[102:103] op_sel_hi:[1,0]
	global_load_dwordx4 v[204:207], v[138:139], off
	v_pk_mul_f32 v[112:113], v[90:91], v[102:103] op_sel_hi:[1,0]
	v_pk_mul_f32 v[114:115], v[92:93], v[102:103] op_sel_hi:[1,0]
	s_waitcnt vmcnt(10)
	v_pk_mul_f32 v[108:109], v[106:107], v[200:201]
	v_pk_mul_f32 v[110:111], v[104:105], v[202:203]
	s_waitcnt vmcnt(6)
	v_mov_b32_e32 v116, v176
	s_waitcnt vmcnt(5)
	v_pk_mul_f32 v[92:93], v[114:115], v[182:183]
	v_pk_mul_f32 v[90:91], v[112:113], v[180:181]
	v_mov_b32_e32 v112, v172
	v_mov_b32_e32 v113, v174
	v_mov_b32_e32 v117, v178
	v_mov_b32_e32 v178, v177
	v_mov_b32_e32 v174, v173
	v_pk_mul_f32 v[114:115], v[112:113], v[90:91]
	v_pk_mul_f32 v[120:121], v[116:117], v[92:93]
	v_pk_mul_f32 v[90:91], v[174:175], v[90:91]
	v_pk_mul_f32 v[92:93], v[178:179], v[92:93]
	v_pk_fma_f32 v[90:91], v[108:109], v[112:113], v[90:91] neg_lo:[0,0,1] neg_hi:[0,0,1]
	v_pk_fma_f32 v[92:93], v[110:111], v[116:117], v[92:93] neg_lo:[0,0,1] neg_hi:[0,0,1]
	v_pk_fma_f32 v[104:105], v[110:111], v[178:179], v[120:121]
	v_pk_fma_f32 v[94:95], v[108:109], v[174:175], v[114:115]
	v_cvt_pk_bf16_f32 v240, v90, v91
	v_cvt_pk_bf16_f32 v241, v92, v93
	v_cvt_pk_bf16_f32 v244, v94, v95
	v_cvt_pk_bf16_f32 v245, v104, v105
	v_pk_mul_f32 v[90:91], v[88:89], v[102:103] op_sel_hi:[1,0]
	v_pk_mul_f32 v[92:93], v[86:87], v[102:103] op_sel_hi:[1,0]
	v_pk_mul_f32 v[104:105], v[82:83], v[102:103] op_sel_hi:[1,0]
	v_pk_mul_f32 v[106:107], v[84:85], v[102:103] op_sel_hi:[1,0]
	s_waitcnt vmcnt(4)
	v_pk_mul_f32 v[94:95], v[92:93], v[184:185]
	v_pk_mul_f32 v[96:97], v[90:91], v[186:187]
	s_waitcnt vmcnt(2)
	v_mov_b32_e32 v108, v192
	s_waitcnt vmcnt(1)
	v_pk_mul_f32 v[84:85], v[106:107], v[198:199]
	v_pk_mul_f32 v[82:83], v[104:105], v[196:197]
	v_mov_b32_e32 v104, v188
	v_mov_b32_e32 v105, v190
	v_mov_b32_e32 v109, v194
	v_mov_b32_e32 v194, v193
	v_mov_b32_e32 v190, v189
	v_pk_mul_f32 v[106:107], v[104:105], v[82:83]
	v_pk_mul_f32 v[110:111], v[108:109], v[84:85]
	v_pk_mul_f32 v[82:83], v[190:191], v[82:83]
	v_pk_mul_f32 v[84:85], v[194:195], v[84:85]
	v_pk_fma_f32 v[82:83], v[94:95], v[104:105], v[82:83] neg_lo:[0,0,1] neg_hi:[0,0,1]
	v_pk_fma_f32 v[84:85], v[96:97], v[108:109], v[84:85] neg_lo:[0,0,1] neg_hi:[0,0,1]
	v_pk_fma_f32 v[90:91], v[96:97], v[194:195], v[110:111]
	v_pk_fma_f32 v[86:87], v[94:95], v[190:191], v[106:107]
	v_cvt_pk_bf16_f32 v242, v82, v83
	v_cvt_pk_bf16_f32 v243, v84, v85
	global_store_dwordx4 v[100:101], v[240:243], off
	v_cvt_pk_bf16_f32 v246, v86, v87
	v_cvt_pk_bf16_f32 v247, v90, v91
	global_store_dwordx4 v[98:99], v[244:247], off
; template <int K> __device__ __forceinline__ float swz(float v) { return __int_as_float(__builtin_amdgcn_ds_swizzle(__float_as_int(v), (K << 10) | 0x1f)); }
; __device__ __forceinline__ float x32_sum(float v) { auto r = __builtin_amdgcn_permlane32_swap(__float_as_uint(v), __float_as_uint(v), false, false); return __uint_as_float(r[0]) + __uint_as_float(r[1]); }
; __device__ __forceinline__ unsigned cvt_pk_bf16(float lo, float hi) { const f32x2c f = {lo, hi}; return __builtin_bit_cast(unsigned, __builtin_convertvector(f, bf16x2c)); }
;     __device__ __forceinline__ void operator()(const f32x4 (&acc)[2][2][4][2], const Unit& u, int wr, int wc, int, int) const {
;     ...
;             for (int m = 0; m < 4; ++m) {
;                 const int row = rowb + ai * HALF + m * 16;
;                 float ss = 0.f;
; #pragma unroll
;                 for (int j = 0; j < 4; ++j) ss += acc[ai][0][m][0][j] * acc[ai][0][m][0][j] + acc[ai][0][m][1][j] * acc[ai][0][m][1][j] + acc[ai][1][m][0][j] * acc[ai][1][m][0][j] + acc[ai][1][m][1][j] * acc[ai][1][m][1][j];
;                 ss += ::swz<16>(ss); ss = ::x32_sum(ss);
;                 float rs = rsqrtf(ss * inv_cnt + 1e-6f) * sc; rs = is_v ? 1.0f : rs;
;                 const int pos = row & 2047, pp = rot ? ((fq & 1) ? (pos & 63) : (pos >> 6)) : 0;
;                 const float* rt = rope + pp * 16;
;                 bf16_t* dst = obase + (unsigned)(row * ostride + ocol);
; #pragma unroll
;                 for (int n = 0; n < 2; ++n) {
;                     const f32x4 g1 = *(const f32x4*)(g + 4 * n), g2 = *(const f32x4*)(g + sbj + 4 * n);
;                     const f32x4 t0 = *(const f32x4*)(rt + 8 * n), t1 = *(const f32x4*)(rt + 8 * n + 4);
;                     const f32x4 c = (f32x4){t0[0], t0[2], t1[0], t1[2]}, s = (f32x4){t0[1], t0[3], t1[1], t1[3]};
;                     const f32x4 a1 = acc[ai][0][m][n] * rs * g1, a2 = acc[ai][1][m][n] * rs * g2;
;                     const f32x4 o1 = a1 * c - a2 * s, o2 = a1 * s + a2 * c;
;                     if (st_ok) { u32x2 w; w.x = cvt_pk_bf16(o1[0], o1[1]); w.y = cvt_pk_bf16(o1[2], o1[3]); *(u32x2*)(dst + 4 * n) = w;
;                         w.x = cvt_pk_bf16(o2[0], o2[1]); w.y = cvt_pk_bf16(o2[2], o2[3]); *(u32x2*)(dst + sbj + 4 * n) = w; }
;                 }
;                 asm volatile("" ::: "memory");
.LBB0_675:
	s_or_b64 exec, exec, s[2:3]
	v_mul_f32_e32 v82, v70, v70
	v_mul_f32_e32 v83, v71, v71
	v_fmac_f32_e32 v82, v78, v78
	v_fmac_f32_e32 v83, v79, v79
	v_fmac_f32_e32 v82, v74, v74
	v_fmac_f32_e32 v83, v75, v75
	v_fmac_f32_e32 v82, v66, v66
	v_fmac_f32_e32 v83, v67, v67
	v_add_f32_e32 v82, v82, v83
	v_mul_f32_e32 v83, v72, v72
	v_fmac_f32_e32 v83, v80, v80
	v_fmac_f32_e32 v83, v76, v76
	v_fmac_f32_e32 v83, v68, v68
	v_add_f32_e32 v82, v83, v82
	v_mul_f32_e32 v83, v73, v73
	v_fmac_f32_e32 v83, v81, v81
	v_fmac_f32_e32 v83, v77, v77
	v_fmac_f32_e32 v83, v69, v69
	v_add_f32_e32 v82, v83, v82
	ds_swizzle_b32 v83, v82 offset:swizzle(SWAP,16)
	v_or_b32_e32 v87, 48, v161
	v_mov_b32_e32 v250, s17
	v_cndmask_b32_e64 v250, v87, v250, s[40:41]
	v_lshlrev_b32_e32 v250, 4, v250
	v_cndmask_b32_e32 v250, 0, v250, vcc
	v_lshlrev_b32_e32 v251, 2, v250
	global_load_dwordx4 v[172:175], v251, s[22:23]
	global_load_dwordx4 v[176:179], v251, s[22:23] offset:16
	global_load_dwordx4 v[180:183], v[140:141], off
	global_load_dwordx4 v[184:187], v[138:139], off offset:16
	global_load_dwordx4 v[188:191], v251, s[22:23] offset:32
	global_load_dwordx4 v[192:195], v251, s[22:23] offset:48
	global_load_dwordx4 v[196:199], v[140:141], off offset:16
	s_waitcnt lgkmcnt(0)
	v_add_f32_e32 v86, v82, v83
	v_mov_b32_e32 v88, v86
	s_nop 1
	v_permlane32_swap_b32_e32 v86, v88
	s_and_saveexec_b64 s[2:3], s[20:21]
	v_or_b32_e32 v82, 48, v160
	v_add_f32_e32 v86, v86, v88
	v_mad_u64_u32 v[82:83], s[42:43], s26, v82, v[142:143]
	v_fmaak_f32 v86, v159, v86, 0x358637bd
	v_cmp_gt_f32_e64 s[42:43], s88, v86
	v_mul_f32_e32 v88, 0x4b800000, v86
	v_mov_b32_e32 v83, v0
	v_cndmask_b32_e64 v86, v86, v88, s[42:43]
	v_rsq_f32_e32 v86, v86
	v_lshl_add_u64 v[84:85], v[82:83], 1, s[60:61]
	s_lshl_b32 s54, s16, 1
	v_lshl_add_u64 v[82:83], v[84:85], 0, s[54:55]
	v_mul_f32_e32 v88, 0x45800000, v86
	v_cndmask_b32_e64 v86, v86, v88, s[42:43]
	v_mul_f32_e32 v86, v143, v86
	v_cndmask_b32_e64 v86, v86, 1.0, s[50:51]
	v_pk_mul_f32 v[88:89], v[80:81], v[86:87] op_sel_hi:[1,0]
	v_pk_mul_f32 v[90:91], v[78:79], v[86:87] op_sel_hi:[1,0]
	global_load_dwordx4 v[200:203], v[138:139], off
	v_pk_mul_f32 v[96:97], v[74:75], v[86:87] op_sel_hi:[1,0]
	v_pk_mul_f32 v[98:99], v[76:77], v[86:87] op_sel_hi:[1,0]
	s_waitcnt vmcnt(10)
	v_pk_mul_f32 v[92:93], v[90:91], v[204:205]
	v_pk_mul_f32 v[94:95], v[88:89], v[206:207]
	s_waitcnt vmcnt(6)
	v_mov_b32_e32 v100, v176
	s_waitcnt vmcnt(5)
	v_pk_mul_f32 v[76:77], v[98:99], v[182:183]
	v_pk_mul_f32 v[74:75], v[96:97], v[180:181]
	v_mov_b32_e32 v96, v172
	v_mov_b32_e32 v97, v174
	v_mov_b32_e32 v101, v178
	v_mov_b32_e32 v178, v177
	v_mov_b32_e32 v174, v173
	v_pk_mul_f32 v[98:99], v[96:97], v[74:75]
	v_pk_mul_f32 v[104:105], v[100:101], v[76:77]
	v_pk_mul_f32 v[74:75], v[174:175], v[74:75]
	v_pk_mul_f32 v[76:77], v[178:179], v[76:77]
	v_pk_fma_f32 v[74:75], v[92:93], v[96:97], v[74:75] neg_lo:[0,0,1] neg_hi:[0,0,1]
	v_pk_fma_f32 v[76:77], v[94:95], v[100:101], v[76:77] neg_lo:[0,0,1] neg_hi:[0,0,1]
	v_pk_fma_f32 v[88:89], v[94:95], v[178:179], v[104:105]
	v_pk_fma_f32 v[78:79], v[92:93], v[174:175], v[98:99]
	v_cvt_pk_bf16_f32 v240, v74, v75
	v_cvt_pk_bf16_f32 v241, v76, v77
	v_cvt_pk_bf16_f32 v244, v78, v79
	v_cvt_pk_bf16_f32 v245, v88, v89
	v_pk_mul_f32 v[74:75], v[72:73], v[86:87] op_sel_hi:[1,0]
	v_pk_mul_f32 v[76:77], v[70:71], v[86:87] op_sel_hi:[1,0]
	v_pk_mul_f32 v[88:89], v[66:67], v[86:87] op_sel_hi:[1,0]
	v_pk_mul_f32 v[90:91], v[68:69], v[86:87] op_sel_hi:[1,0]
	s_waitcnt vmcnt(4)
	v_pk_mul_f32 v[78:79], v[76:77], v[184:185]
	v_pk_mul_f32 v[80:81], v[74:75], v[186:187]
	s_waitcnt vmcnt(2)
	v_mov_b32_e32 v92, v192
	s_waitcnt vmcnt(1)
	v_pk_mul_f32 v[68:69], v[90:91], v[198:199]
	v_pk_mul_f32 v[66:67], v[88:89], v[196:197]
	v_mov_b32_e32 v88, v188
	v_mov_b32_e32 v89, v190
	v_mov_b32_e32 v93, v194
	v_mov_b32_e32 v194, v193
	v_mov_b32_e32 v190, v189
	v_pk_mul_f32 v[90:91], v[88:89], v[66:67]
	v_pk_mul_f32 v[94:95], v[92:93], v[68:69]
	v_pk_mul_f32 v[66:67], v[190:191], v[66:67]
	v_pk_mul_f32 v[68:69], v[194:195], v[68:69]
	v_pk_fma_f32 v[66:67], v[78:79], v[88:89], v[66:67] neg_lo:[0,0,1] neg_hi:[0,0,1]
	v_pk_fma_f32 v[68:69], v[80:81], v[92:93], v[68:69] neg_lo:[0,0,1] neg_hi:[0,0,1]
	v_pk_fma_f32 v[74:75], v[80:81], v[194:195], v[94:95]
	v_pk_fma_f32 v[70:71], v[78:79], v[190:191], v[90:91]
	v_cvt_pk_bf16_f32 v242, v66, v67
	v_cvt_pk_bf16_f32 v243, v68, v69
	global_store_dwordx4 v[84:85], v[240:243], off
	v_cvt_pk_bf16_f32 v246, v70, v71
	v_cvt_pk_bf16_f32 v247, v74, v75
	global_store_dwordx4 v[82:83], v[244:247], off
; template <int K> __device__ __forceinline__ float swz(float v) { return __int_as_float(__builtin_amdgcn_ds_swizzle(__float_as_int(v), (K << 10) | 0x1f)); }
; __device__ __forceinline__ float x32_sum(float v) { auto r = __builtin_amdgcn_permlane32_swap(__float_as_uint(v), __float_as_uint(v), false, false); return __uint_as_float(r[0]) + __uint_as_float(r[1]); }
; __device__ __forceinline__ unsigned cvt_pk_bf16(float lo, float hi) { const f32x2c f = {lo, hi}; return __builtin_bit_cast(unsigned, __builtin_convertvector(f, bf16x2c)); }
;     __device__ __forceinline__ void operator()(const f32x4 (&acc)[2][2][4][2], const Unit& u, int wr, int wc, int, int) const {
;     ...
;             for (int m = 0; m < 4; ++m) {
;                 const int row = rowb + ai * HALF + m * 16;
;                 float ss = 0.f;
; #pragma unroll
;                 for (int j = 0; j < 4; ++j) ss += acc[ai][0][m][0][j] * acc[ai][0][m][0][j] + acc[ai][0][m][1][j] * acc[ai][0][m][1][j] + acc[ai][1][m][0][j] * acc[ai][1][m][0][j] + acc[ai][1][m][1][j] * acc[ai][1][m][1][j];
;                 ss += ::swz<16>(ss); ss = ::x32_sum(ss);
;                 float rs = rsqrtf(ss * inv_cnt + 1e-6f) * sc; rs = is_v ? 1.0f : rs;
;                 const int pos = row & 2047, pp = rot ? ((fq & 1) ? (pos & 63) : (pos >> 6)) : 0;
;                 const float* rt = rope + pp * 16;
;                 bf16_t* dst = obase + (unsigned)(row * ostride + ocol);
; #pragma unroll
;                 for (int n = 0; n < 2; ++n) {
;                     const f32x4 g1 = *(const f32x4*)(g + 4 * n), g2 = *(const f32x4*)(g + sbj + 4 * n);
;                     const f32x4 t0 = *(const f32x4*)(rt + 8 * n), t1 = *(const f32x4*)(rt + 8 * n + 4);
;                     const f32x4 c = (f32x4){t0[0], t0[2], t1[0], t1[2]}, s = (f32x4){t0[1], t0[3], t1[1], t1[3]};
;                     const f32x4 a1 = acc[ai][0][m][n] * rs * g1, a2 = acc[ai][1][m][n] * rs * g2;
;                     const f32x4 o1 = a1 * c - a2 * s, o2 = a1 * s + a2 * c;
;                     if (st_ok) { u32x2 w; w.x = cvt_pk_bf16(o1[0], o1[1]); w.y = cvt_pk_bf16(o1[2], o1[3]); *(u32x2*)(dst + 4 * n) = w;
;                         w.x = cvt_pk_bf16(o2[0], o2[1]); w.y = cvt_pk_bf16(o2[2], o2[3]); *(u32x2*)(dst + sbj + 4 * n) = w; }
;                 }
;                 asm volatile("" ::: "memory");
.LBB0_677:
	s_or_b64 exec, exec, s[2:3]
	v_mul_f32_e32 v66, v54, v54
	v_mul_f32_e32 v67, v55, v55
	v_fmac_f32_e32 v66, v62, v62
	v_fmac_f32_e32 v67, v63, v63
	v_fmac_f32_e32 v66, v58, v58
	v_fmac_f32_e32 v67, v59, v59
	v_fmac_f32_e32 v66, v50, v50
	v_fmac_f32_e32 v67, v51, v51
	v_add_f32_e32 v66, v66, v67
	v_mul_f32_e32 v67, v56, v56
	v_fmac_f32_e32 v67, v64, v64
	v_fmac_f32_e32 v67, v60, v60
	v_fmac_f32_e32 v67, v52, v52
	v_add_f32_e32 v66, v67, v66
	v_mul_f32_e32 v67, v57, v57
	v_fmac_f32_e32 v67, v65, v65
	v_fmac_f32_e32 v67, v61, v61
	v_fmac_f32_e32 v67, v53, v53
	v_add_f32_e32 v67, v67, v66
	ds_swizzle_b32 v68, v67 offset:swizzle(SWAP,16)
	v_add_u32_e32 v66, 0x80, v160
	v_bfe_u32 v71, v66, 6, 5
	v_cndmask_b32_e64 v248, v161, v71, s[40:41]
	v_lshlrev_b32_e32 v248, 4, v248
	v_cndmask_b32_e32 v248, 0, v248, vcc
	v_lshlrev_b32_e32 v249, 2, v248
	global_load_dwordx4 v[172:175], v249, s[22:23]
	global_load_dwordx4 v[176:179], v249, s[22:23] offset:16
	global_load_dwordx4 v[180:183], v[140:141], off
	global_load_dwordx4 v[184:187], v[138:139], off offset:16
	global_load_dwordx4 v[188:191], v249, s[22:23] offset:32
	global_load_dwordx4 v[192:195], v249, s[22:23] offset:48
	global_load_dwordx4 v[196:199], v[140:141], off offset:16
	s_waitcnt lgkmcnt(0)
	v_add_f32_e32 v70, v67, v68
	v_mov_b32_e32 v72, v70
	s_nop 1
	v_permlane32_swap_b32_e32 v70, v72
	s_and_saveexec_b64 s[2:3], s[20:21]
	v_add_f32_e32 v70, v70, v72
	v_mad_u64_u32 v[66:67], s[42:43], s26, v66, v[142:143]
	v_fmaak_f32 v70, v159, v70, 0x358637bd
	v_cmp_gt_f32_e64 s[42:43], s88, v70
	v_mul_f32_e32 v72, 0x4b800000, v70
	v_mov_b32_e32 v67, v0
	v_cndmask_b32_e64 v70, v70, v72, s[42:43]
	v_rsq_f32_e32 v70, v70
	v_lshl_add_u64 v[68:69], v[66:67], 1, s[60:61]
	s_lshl_b32 s54, s16, 1
	v_lshl_add_u64 v[66:67], v[68:69], 0, s[54:55]
	v_mul_f32_e32 v72, 0x45800000, v70
	v_cndmask_b32_e64 v70, v70, v72, s[42:43]
	v_mul_f32_e32 v70, v143, v70
	v_cndmask_b32_e64 v70, v70, 1.0, s[50:51]
	v_pk_mul_f32 v[72:73], v[64:65], v[70:71] op_sel_hi:[1,0]
	v_pk_mul_f32 v[74:75], v[62:63], v[70:71] op_sel_hi:[1,0]
	global_load_dwordx4 v[204:207], v[138:139], off
	v_pk_mul_f32 v[80:81], v[58:59], v[70:71] op_sel_hi:[1,0]
	v_pk_mul_f32 v[82:83], v[60:61], v[70:71] op_sel_hi:[1,0]
	s_waitcnt vmcnt(10)
	v_pk_mul_f32 v[76:77], v[74:75], v[200:201]
	v_pk_mul_f32 v[78:79], v[72:73], v[202:203]
	v_cndmask_b32_e64 v251, v119, v71, s[40:41]
	v_lshlrev_b32_e32 v251, 4, v251
	v_cndmask_b32_e32 v251, 0, v251, vcc
	v_lshlrev_b32_e32 v251, 2, v251
	global_load_dwordx4 v[200:203], v251, s[22:23]
	global_load_dwordx4 v[212:215], v251, s[22:23] offset:16
	global_load_dwordx4 v[224:227], v[140:141], off
	s_waitcnt vmcnt(9)
	v_mov_b32_e32 v84, v176
	s_waitcnt vmcnt(8)
	v_pk_mul_f32 v[60:61], v[82:83], v[182:183]
	v_pk_mul_f32 v[58:59], v[80:81], v[180:181]
	v_mov_b32_e32 v80, v172
	v_mov_b32_e32 v81, v174
	v_mov_b32_e32 v85, v178
	v_mov_b32_e32 v178, v177
	v_mov_b32_e32 v174, v173
	v_pk_mul_f32 v[82:83], v[80:81], v[58:59]
	v_pk_mul_f32 v[88:89], v[84:85], v[60:61]
	v_pk_mul_f32 v[58:59], v[174:175], v[58:59]
	v_pk_mul_f32 v[60:61], v[178:179], v[60:61]
	v_pk_fma_f32 v[58:59], v[76:77], v[80:81], v[58:59] neg_lo:[0,0,1] neg_hi:[0,0,1]
	v_pk_fma_f32 v[60:61], v[78:79], v[84:85], v[60:61] neg_lo:[0,0,1] neg_hi:[0,0,1]
	v_pk_fma_f32 v[72:73], v[78:79], v[178:179], v[88:89]
	v_pk_fma_f32 v[62:63], v[76:77], v[174:175], v[82:83]
	v_cvt_pk_bf16_f32 v240, v58, v59
	v_cvt_pk_bf16_f32 v241, v60, v61
	v_cvt_pk_bf16_f32 v244, v62, v63
	v_cvt_pk_bf16_f32 v245, v72, v73
	v_pk_mul_f32 v[58:59], v[56:57], v[70:71] op_sel_hi:[1,0]
	v_pk_mul_f32 v[60:61], v[54:55], v[70:71] op_sel_hi:[1,0]
	global_load_dwordx4 v[172:175], v[138:139], off offset:16
	v_pk_mul_f32 v[72:73], v[50:51], v[70:71] op_sel_hi:[1,0]
	v_pk_mul_f32 v[74:75], v[52:53], v[70:71] op_sel_hi:[1,0]
	s_waitcnt vmcnt(8)
	v_pk_mul_f32 v[62:63], v[60:61], v[184:185]
	v_pk_mul_f32 v[64:65], v[58:59], v[186:187]
	global_load_dwordx4 v[176:179], v251, s[22:23] offset:32
	global_load_dwordx4 v[180:183], v251, s[22:23] offset:48
	global_load_dwordx4 v[184:187], v[140:141], off offset:16
	s_waitcnt vmcnt(9)
	v_mov_b32_e32 v76, v192
	s_waitcnt vmcnt(8)
	v_pk_mul_f32 v[52:53], v[74:75], v[198:199]
	v_pk_mul_f32 v[50:51], v[72:73], v[196:197]
	v_mov_b32_e32 v72, v188
	v_mov_b32_e32 v73, v190
	v_mov_b32_e32 v77, v194
	v_mov_b32_e32 v194, v193
	v_mov_b32_e32 v190, v189
	v_pk_mul_f32 v[74:75], v[72:73], v[50:51]
	v_pk_mul_f32 v[78:79], v[76:77], v[52:53]
	v_pk_mul_f32 v[50:51], v[190:191], v[50:51]
	v_pk_mul_f32 v[52:53], v[194:195], v[52:53]
	v_pk_fma_f32 v[50:51], v[62:63], v[72:73], v[50:51] neg_lo:[0,0,1] neg_hi:[0,0,1]
	v_pk_fma_f32 v[52:53], v[64:65], v[76:77], v[52:53] neg_lo:[0,0,1] neg_hi:[0,0,1]
	v_pk_fma_f32 v[58:59], v[64:65], v[194:195], v[78:79]
	v_pk_fma_f32 v[54:55], v[62:63], v[190:191], v[74:75]
	v_cvt_pk_bf16_f32 v242, v50, v51
	v_cvt_pk_bf16_f32 v243, v52, v53
	global_store_dwordx4 v[68:69], v[240:243], off
	v_cvt_pk_bf16_f32 v246, v54, v55
	v_cvt_pk_bf16_f32 v247, v58, v59
	global_store_dwordx4 v[66:67], v[244:247], off
; template <int K> __device__ __forceinline__ float swz(float v) { return __int_as_float(__builtin_amdgcn_ds_swizzle(__float_as_int(v), (K << 10) | 0x1f)); }
; __device__ __forceinline__ float x32_sum(float v) { auto r = __builtin_amdgcn_permlane32_swap(__float_as_uint(v), __float_as_uint(v), false, false); return __uint_as_float(r[0]) + __uint_as_float(r[1]); }
; __device__ __forceinline__ unsigned cvt_pk_bf16(float lo, float hi) { const f32x2c f = {lo, hi}; return __builtin_bit_cast(unsigned, __builtin_convertvector(f, bf16x2c)); }
;     __device__ __forceinline__ void operator()(const f32x4 (&acc)[2][2][4][2], const Unit& u, int wr, int wc, int, int) const {
;     ...
;             for (int m = 0; m < 4; ++m) {
;                 const int row = rowb + ai * HALF + m * 16;
;                 float ss = 0.f;
; #pragma unroll
;                 for (int j = 0; j < 4; ++j) ss += acc[ai][0][m][0][j] * acc[ai][0][m][0][j] + acc[ai][0][m][1][j] * acc[ai][0][m][1][j] + acc[ai][1][m][0][j] * acc[ai][1][m][0][j] + acc[ai][1][m][1][j] * acc[ai][1][m][1][j];
;                 ss += ::swz<16>(ss); ss = ::x32_sum(ss);
;                 float rs = rsqrtf(ss * inv_cnt + 1e-6f) * sc; rs = is_v ? 1.0f : rs;
;                 const int pos = row & 2047, pp = rot ? ((fq & 1) ? (pos & 63) : (pos >> 6)) : 0;
;                 const float* rt = rope + pp * 16;
;                 bf16_t* dst = obase + (unsigned)(row * ostride + ocol);
; #pragma unroll
;                 for (int n = 0; n < 2; ++n) {
;                     const f32x4 g1 = *(const f32x4*)(g + 4 * n), g2 = *(const f32x4*)(g + sbj + 4 * n);
;                     const f32x4 t0 = *(const f32x4*)(rt + 8 * n), t1 = *(const f32x4*)(rt + 8 * n + 4);
;                     const f32x4 c = (f32x4){t0[0], t0[2], t1[0], t1[2]}, s = (f32x4){t0[1], t0[3], t1[1], t1[3]};
;                     const f32x4 a1 = acc[ai][0][m][n] * rs * g1, a2 = acc[ai][1][m][n] * rs * g2;
;                     const f32x4 o1 = a1 * c - a2 * s, o2 = a1 * s + a2 * c;
;                     if (st_ok) { u32x2 w; w.x = cvt_pk_bf16(o1[0], o1[1]); w.y = cvt_pk_bf16(o1[2], o1[3]); *(u32x2*)(dst + 4 * n) = w;
;                         w.x = cvt_pk_bf16(o2[0], o2[1]); w.y = cvt_pk_bf16(o2[2], o2[3]); *(u32x2*)(dst + sbj + 4 * n) = w; }
;                 }
;                 asm volatile("" ::: "memory");
.LBB0_679:
	s_or_b64 exec, exec, s[2:3]
	v_mul_f32_e32 v50, v38, v38
	v_mul_f32_e32 v51, v39, v39
	v_fmac_f32_e32 v50, v46, v46
	v_fmac_f32_e32 v51, v47, v47
	v_fmac_f32_e32 v50, v42, v42
	v_fmac_f32_e32 v51, v43, v43
	v_fmac_f32_e32 v50, v34, v34
	v_fmac_f32_e32 v51, v35, v35
	v_add_f32_e32 v50, v50, v51
	v_mul_f32_e32 v51, v40, v40
	v_fmac_f32_e32 v51, v48, v48
	v_fmac_f32_e32 v51, v44, v44
	v_fmac_f32_e32 v51, v36, v36
	v_add_f32_e32 v50, v51, v50
	v_mul_f32_e32 v51, v41, v41
	v_fmac_f32_e32 v51, v49, v49
	v_fmac_f32_e32 v51, v45, v45
	v_fmac_f32_e32 v51, v37, v37
	v_add_f32_e32 v50, v51, v50
	ds_swizzle_b32 v51, v50 offset:swizzle(SWAP,16)
	s_waitcnt lgkmcnt(0)
	v_add_f32_e32 v54, v50, v51
	v_mov_b32_e32 v55, v54
	s_nop 1
	v_permlane32_swap_b32_e32 v54, v55
	s_and_saveexec_b64 s[2:3], s[20:21]
	v_add_u32_e32 v50, 0x90, v160
	v_add_f32_e32 v54, v54, v55
	v_mad_u64_u32 v[50:51], s[42:43], s26, v50, v[142:143]
	v_fmaak_f32 v54, v159, v54, 0x358637bd
	v_cmp_gt_f32_e64 s[42:43], s88, v54
	v_mul_f32_e32 v55, 0x4b800000, v54
	v_mov_b32_e32 v51, v0
	v_cndmask_b32_e64 v54, v54, v55, s[42:43]
	v_rsq_f32_e32 v54, v54
	v_lshl_add_u64 v[52:53], v[50:51], 1, s[60:61]
	s_lshl_b32 s54, s16, 1
	v_lshl_add_u64 v[50:51], v[52:53], 0, s[54:55]
	v_mul_f32_e32 v55, 0x45800000, v54
	v_cndmask_b32_e64 v54, v54, v55, s[42:43]
	v_mul_f32_e32 v54, v143, v54
	v_cndmask_b32_e64 v54, v54, 1.0, s[50:51]
	v_pk_mul_f32 v[56:57], v[48:49], v[54:55] op_sel_hi:[1,0]
	v_pk_mul_f32 v[58:59], v[46:47], v[54:55] op_sel_hi:[1,0]
	global_load_dwordx4 v[188:191], v[138:139], off
	v_pk_mul_f32 v[64:65], v[42:43], v[54:55] op_sel_hi:[1,0]
	v_pk_mul_f32 v[66:67], v[44:45], v[54:55] op_sel_hi:[1,0]
	s_waitcnt vmcnt(10)
	v_pk_mul_f32 v[60:61], v[58:59], v[204:205]
	v_pk_mul_f32 v[62:63], v[56:57], v[206:207]
	v_cndmask_b32_e64 v249, v103, v71, s[40:41]
	v_lshlrev_b32_e32 v249, 4, v249
	v_cndmask_b32_e32 v249, 0, v249, vcc
	v_lshlrev_b32_e32 v249, 2, v249
	global_load_dwordx4 v[192:195], v249, s[22:23]
	global_load_dwordx4 v[196:199], v249, s[22:23] offset:16
	global_load_dwordx4 v[204:207], v[140:141], off
	s_waitcnt vmcnt(11)
	v_mov_b32_e32 v68, v212
	s_waitcnt vmcnt(10)
	v_pk_mul_f32 v[44:45], v[66:67], v[226:227]
	v_pk_mul_f32 v[42:43], v[64:65], v[224:225]
	v_mov_b32_e32 v64, v200
	v_mov_b32_e32 v65, v202
	v_mov_b32_e32 v69, v214
	v_mov_b32_e32 v214, v213
	v_mov_b32_e32 v202, v201
	v_pk_mul_f32 v[66:67], v[64:65], v[42:43]
	v_pk_mul_f32 v[72:73], v[68:69], v[44:45]
	v_pk_mul_f32 v[42:43], v[202:203], v[42:43]
	v_pk_mul_f32 v[44:45], v[214:215], v[44:45]
	v_pk_fma_f32 v[42:43], v[60:61], v[64:65], v[42:43] neg_lo:[0,0,1] neg_hi:[0,0,1]
	v_pk_fma_f32 v[44:45], v[62:63], v[68:69], v[44:45] neg_lo:[0,0,1] neg_hi:[0,0,1]
	v_pk_fma_f32 v[56:57], v[62:63], v[214:215], v[72:73]
	v_pk_fma_f32 v[46:47], v[60:61], v[202:203], v[66:67]
	v_cvt_pk_bf16_f32 v240, v42, v43
	v_cvt_pk_bf16_f32 v241, v44, v45
	v_cvt_pk_bf16_f32 v244, v46, v47
	v_cvt_pk_bf16_f32 v245, v56, v57
	v_pk_mul_f32 v[42:43], v[40:41], v[54:55] op_sel_hi:[1,0]
	v_pk_mul_f32 v[44:45], v[38:39], v[54:55] op_sel_hi:[1,0]
	global_load_dwordx4 v[200:203], v[138:139], off offset:16
	v_pk_mul_f32 v[56:57], v[34:35], v[54:55] op_sel_hi:[1,0]
	s_waitcnt vmcnt(10)
	v_pk_mul_f32 v[46:47], v[44:45], v[172:173]
	v_pk_mul_f32 v[48:49], v[42:43], v[174:175]
	global_load_dwordx4 v[172:175], v249, s[22:23] offset:32
	global_load_dwordx4 v[212:215], v249, s[22:23] offset:48
	v_pk_mul_f32 v[54:55], v[36:37], v[54:55] op_sel_hi:[1,0]
	global_load_dwordx4 v[224:227], v[140:141], off offset:16
	s_waitcnt vmcnt(11)
	v_mov_b32_e32 v58, v180
	v_mov_b32_e32 v59, v182
	s_waitcnt vmcnt(10)
	v_pk_mul_f32 v[36:37], v[54:55], v[186:187]
	v_pk_mul_f32 v[34:35], v[56:57], v[184:185]
	v_mov_b32_e32 v54, v176
	v_mov_b32_e32 v55, v178
	v_mov_b32_e32 v182, v181
	v_mov_b32_e32 v178, v177
	v_pk_mul_f32 v[56:57], v[54:55], v[34:35]
	v_pk_mul_f32 v[60:61], v[58:59], v[36:37]
	v_pk_mul_f32 v[34:35], v[178:179], v[34:35]
	v_pk_mul_f32 v[36:37], v[182:183], v[36:37]
	v_pk_fma_f32 v[34:35], v[46:47], v[54:55], v[34:35] neg_lo:[0,0,1] neg_hi:[0,0,1]
	v_pk_fma_f32 v[36:37], v[48:49], v[58:59], v[36:37] neg_lo:[0,0,1] neg_hi:[0,0,1]
	v_pk_fma_f32 v[42:43], v[48:49], v[182:183], v[60:61]
	v_pk_fma_f32 v[38:39], v[46:47], v[178:179], v[56:57]
	v_cvt_pk_bf16_f32 v242, v34, v35
	v_cvt_pk_bf16_f32 v243, v36, v37
	global_store_dwordx4 v[52:53], v[240:243], off
	v_cvt_pk_bf16_f32 v246, v38, v39
	v_cvt_pk_bf16_f32 v247, v42, v43
	global_store_dwordx4 v[50:51], v[244:247], off
; template <int K> __device__ __forceinline__ float swz(float v) { return __int_as_float(__builtin_amdgcn_ds_swizzle(__float_as_int(v), (K << 10) | 0x1f)); }
; __device__ __forceinline__ float x32_sum(float v) { auto r = __builtin_amdgcn_permlane32_swap(__float_as_uint(v), __float_as_uint(v), false, false); return __uint_as_float(r[0]) + __uint_as_float(r[1]); }
; __device__ __forceinline__ unsigned cvt_pk_bf16(float lo, float hi) { const f32x2c f = {lo, hi}; return __builtin_bit_cast(unsigned, __builtin_convertvector(f, bf16x2c)); }
;     __device__ __forceinline__ void operator()(const f32x4 (&acc)[2][2][4][2], const Unit& u, int wr, int wc, int, int) const {
;     ...
;             for (int m = 0; m < 4; ++m) {
;                 const int row = rowb + ai * HALF + m * 16;
;                 float ss = 0.f;
; #pragma unroll
;                 for (int j = 0; j < 4; ++j) ss += acc[ai][0][m][0][j] * acc[ai][0][m][0][j] + acc[ai][0][m][1][j] * acc[ai][0][m][1][j] + acc[ai][1][m][0][j] * acc[ai][1][m][0][j] + acc[ai][1][m][1][j] * acc[ai][1][m][1][j];
;                 ss += ::swz<16>(ss); ss = ::x32_sum(ss);
;                 float rs = rsqrtf(ss * inv_cnt + 1e-6f) * sc; rs = is_v ? 1.0f : rs;
;                 const int pos = row & 2047, pp = rot ? ((fq & 1) ? (pos & 63) : (pos >> 6)) : 0;
;                 const float* rt = rope + pp * 16;
;                 bf16_t* dst = obase + (unsigned)(row * ostride + ocol);
; #pragma unroll
;                 for (int n = 0; n < 2; ++n) {
;                     const f32x4 g1 = *(const f32x4*)(g + 4 * n), g2 = *(const f32x4*)(g + sbj + 4 * n);
;                     const f32x4 t0 = *(const f32x4*)(rt + 8 * n), t1 = *(const f32x4*)(rt + 8 * n + 4);
;                     const f32x4 c = (f32x4){t0[0], t0[2], t1[0], t1[2]}, s = (f32x4){t0[1], t0[3], t1[1], t1[3]};
;                     const f32x4 a1 = acc[ai][0][m][n] * rs * g1, a2 = acc[ai][1][m][n] * rs * g2;
;                     const f32x4 o1 = a1 * c - a2 * s, o2 = a1 * s + a2 * c;
;                     if (st_ok) { u32x2 w; w.x = cvt_pk_bf16(o1[0], o1[1]); w.y = cvt_pk_bf16(o1[2], o1[3]); *(u32x2*)(dst + 4 * n) = w;
;                         w.x = cvt_pk_bf16(o2[0], o2[1]); w.y = cvt_pk_bf16(o2[2], o2[3]); *(u32x2*)(dst + sbj + 4 * n) = w; }
;                 }
;                 asm volatile("" ::: "memory");
.LBB0_681:
	s_or_b64 exec, exec, s[2:3]
	v_mul_f32_e32 v34, v22, v22
	v_mul_f32_e32 v35, v23, v23
	v_fmac_f32_e32 v34, v30, v30
	v_fmac_f32_e32 v35, v31, v31
	v_fmac_f32_e32 v34, v26, v26
	v_fmac_f32_e32 v35, v27, v27
	v_fmac_f32_e32 v34, v18, v18
	v_fmac_f32_e32 v35, v19, v19
	v_add_f32_e32 v34, v34, v35
	v_mul_f32_e32 v35, v24, v24
	v_fmac_f32_e32 v35, v32, v32
	v_fmac_f32_e32 v35, v28, v28
	v_fmac_f32_e32 v35, v20, v20
	v_add_f32_e32 v34, v35, v34
	v_mul_f32_e32 v35, v25, v25
	v_fmac_f32_e32 v35, v33, v33
	v_fmac_f32_e32 v35, v29, v29
	v_fmac_f32_e32 v35, v21, v21
	v_add_f32_e32 v34, v35, v34
	ds_swizzle_b32 v35, v34 offset:swizzle(SWAP,16)
	s_waitcnt lgkmcnt(0)
	v_add_f32_e32 v38, v34, v35
	v_mov_b32_e32 v39, v38
	s_nop 1
	v_permlane32_swap_b32_e32 v38, v39
	s_and_saveexec_b64 s[2:3], s[20:21]
	v_add_u32_e32 v34, 0xa0, v160
	v_add_f32_e32 v38, v38, v39
	v_mad_u64_u32 v[34:35], s[42:43], s26, v34, v[142:143]
	v_fmaak_f32 v38, v159, v38, 0x358637bd
	v_cmp_gt_f32_e64 s[42:43], s88, v38
	v_mul_f32_e32 v39, 0x4b800000, v38
	v_mov_b32_e32 v35, v0
	v_cndmask_b32_e64 v38, v38, v39, s[42:43]
	v_rsq_f32_e32 v38, v38
	v_lshl_add_u64 v[36:37], v[34:35], 1, s[60:61]
	s_lshl_b32 s54, s16, 1
	v_lshl_add_u64 v[34:35], v[36:37], 0, s[54:55]
	v_mul_f32_e32 v39, 0x45800000, v38
	v_cndmask_b32_e64 v38, v38, v39, s[42:43]
	v_mul_f32_e32 v38, v143, v38
	v_cndmask_b32_e64 v38, v38, 1.0, s[50:51]
	v_pk_mul_f32 v[40:41], v[32:33], v[38:39] op_sel_hi:[1,0]
	v_pk_mul_f32 v[42:43], v[30:31], v[38:39] op_sel_hi:[1,0]
	global_load_dwordx4 v[176:179], v[138:139], off
	v_pk_mul_f32 v[48:49], v[26:27], v[38:39] op_sel_hi:[1,0]
	v_pk_mul_f32 v[50:51], v[28:29], v[38:39] op_sel_hi:[1,0]
	s_waitcnt vmcnt(10)
	v_pk_mul_f32 v[44:45], v[42:43], v[188:189]
	v_pk_mul_f32 v[46:47], v[40:41], v[190:191]
	v_cndmask_b32_e64 v251, v87, v71, s[40:41]
	v_lshlrev_b32_e32 v251, 4, v251
	v_cndmask_b32_e32 v251, 0, v251, vcc
	v_lshlrev_b32_e32 v251, 2, v251
	global_load_dwordx4 v[180:183], v251, s[22:23]
	global_load_dwordx4 v[184:187], v251, s[22:23] offset:16
	global_load_dwordx4 v[188:191], v[140:141], off
	s_waitcnt vmcnt(11)
	v_mov_b32_e32 v52, v196
	s_waitcnt vmcnt(10)
	v_pk_mul_f32 v[28:29], v[50:51], v[206:207]
	v_pk_mul_f32 v[26:27], v[48:49], v[204:205]
	v_mov_b32_e32 v48, v192
	v_mov_b32_e32 v49, v194
	v_mov_b32_e32 v53, v198
	v_mov_b32_e32 v198, v197
	v_mov_b32_e32 v194, v193
	v_pk_mul_f32 v[50:51], v[48:49], v[26:27]
	v_pk_mul_f32 v[54:55], v[52:53], v[28:29]
	v_pk_mul_f32 v[26:27], v[194:195], v[26:27]
	v_pk_mul_f32 v[28:29], v[198:199], v[28:29]
	v_pk_fma_f32 v[26:27], v[44:45], v[48:49], v[26:27] neg_lo:[0,0,1] neg_hi:[0,0,1]
	v_pk_fma_f32 v[28:29], v[46:47], v[52:53], v[28:29] neg_lo:[0,0,1] neg_hi:[0,0,1]
	v_pk_fma_f32 v[40:41], v[46:47], v[198:199], v[54:55]
	v_pk_fma_f32 v[30:31], v[44:45], v[194:195], v[50:51]
	v_cvt_pk_bf16_f32 v240, v26, v27
	v_cvt_pk_bf16_f32 v241, v28, v29
	v_cvt_pk_bf16_f32 v244, v30, v31
	v_cvt_pk_bf16_f32 v245, v40, v41
	v_pk_mul_f32 v[26:27], v[24:25], v[38:39] op_sel_hi:[1,0]
	v_pk_mul_f32 v[28:29], v[22:23], v[38:39] op_sel_hi:[1,0]
	global_load_dwordx4 v[192:195], v[138:139], off offset:16
	v_pk_mul_f32 v[40:41], v[18:19], v[38:39] op_sel_hi:[1,0]
	s_waitcnt vmcnt(10)
	v_pk_mul_f32 v[30:31], v[28:29], v[200:201]
	v_pk_mul_f32 v[32:33], v[26:27], v[202:203]
	global_load_dwordx4 v[196:199], v251, s[22:23] offset:32
	global_load_dwordx4 v[200:203], v251, s[22:23] offset:48
	v_pk_mul_f32 v[38:39], v[20:21], v[38:39] op_sel_hi:[1,0]
	global_load_dwordx4 v[204:207], v[140:141], off offset:16
	s_waitcnt vmcnt(11)
	v_mov_b32_e32 v42, v212
	v_mov_b32_e32 v43, v214
	s_waitcnt vmcnt(10)
	v_pk_mul_f32 v[20:21], v[38:39], v[226:227]
	v_pk_mul_f32 v[18:19], v[40:41], v[224:225]
	v_mov_b32_e32 v38, v172
	v_mov_b32_e32 v39, v174
	v_mov_b32_e32 v214, v213
	v_mov_b32_e32 v174, v173
	v_pk_mul_f32 v[40:41], v[38:39], v[18:19]
	v_pk_mul_f32 v[44:45], v[42:43], v[20:21]
	v_pk_mul_f32 v[18:19], v[174:175], v[18:19]
	v_pk_mul_f32 v[20:21], v[214:215], v[20:21]
	v_pk_fma_f32 v[18:19], v[30:31], v[38:39], v[18:19] neg_lo:[0,0,1] neg_hi:[0,0,1]
	v_pk_fma_f32 v[20:21], v[32:33], v[42:43], v[20:21] neg_lo:[0,0,1] neg_hi:[0,0,1]
	v_pk_fma_f32 v[26:27], v[32:33], v[214:215], v[44:45]
	v_pk_fma_f32 v[22:23], v[30:31], v[174:175], v[40:41]
	v_cvt_pk_bf16_f32 v242, v18, v19
	v_cvt_pk_bf16_f32 v243, v20, v21
	global_store_dwordx4 v[36:37], v[240:243], off
	v_cvt_pk_bf16_f32 v246, v22, v23
	v_cvt_pk_bf16_f32 v247, v26, v27
	global_store_dwordx4 v[34:35], v[244:247], off
; template <int K> __device__ __forceinline__ float swz(float v) { return __int_as_float(__builtin_amdgcn_ds_swizzle(__float_as_int(v), (K << 10) | 0x1f)); }
; __device__ __forceinline__ float x32_sum(float v) { auto r = __builtin_amdgcn_permlane32_swap(__float_as_uint(v), __float_as_uint(v), false, false); return __uint_as_float(r[0]) + __uint_as_float(r[1]); }
; __device__ __forceinline__ unsigned cvt_pk_bf16(float lo, float hi) { const f32x2c f = {lo, hi}; return __builtin_bit_cast(unsigned, __builtin_convertvector(f, bf16x2c)); }
;     __device__ __forceinline__ void operator()(const f32x4 (&acc)[2][2][4][2], const Unit& u, int wr, int wc, int, int) const {
;     ...
;             for (int m = 0; m < 4; ++m) {
;                 const int row = rowb + ai * HALF + m * 16;
;                 float ss = 0.f;
; #pragma unroll
;                 for (int j = 0; j < 4; ++j) ss += acc[ai][0][m][0][j] * acc[ai][0][m][0][j] + acc[ai][0][m][1][j] * acc[ai][0][m][1][j] + acc[ai][1][m][0][j] * acc[ai][1][m][0][j] + acc[ai][1][m][1][j] * acc[ai][1][m][1][j];
;                 ss += ::swz<16>(ss); ss = ::x32_sum(ss);
;                 float rs = rsqrtf(ss * inv_cnt + 1e-6f) * sc; rs = is_v ? 1.0f : rs;
;                 const int pos = row & 2047, pp = rot ? ((fq & 1) ? (pos & 63) : (pos >> 6)) : 0;
;                 const float* rt = rope + pp * 16;
;                 bf16_t* dst = obase + (unsigned)(row * ostride + ocol);
; #pragma unroll
;                 for (int n = 0; n < 2; ++n) {
;                     const f32x4 g1 = *(const f32x4*)(g + 4 * n), g2 = *(const f32x4*)(g + sbj + 4 * n);
;                     const f32x4 t0 = *(const f32x4*)(rt + 8 * n), t1 = *(const f32x4*)(rt + 8 * n + 4);
;                     const f32x4 c = (f32x4){t0[0], t0[2], t1[0], t1[2]}, s = (f32x4){t0[1], t0[3], t1[1], t1[3]};
;                     const f32x4 a1 = acc[ai][0][m][n] * rs * g1, a2 = acc[ai][1][m][n] * rs * g2;
;                     const f32x4 o1 = a1 * c - a2 * s, o2 = a1 * s + a2 * c;
;                     if (st_ok) { u32x2 w; w.x = cvt_pk_bf16(o1[0], o1[1]); w.y = cvt_pk_bf16(o1[2], o1[3]); *(u32x2*)(dst + 4 * n) = w;
;                         w.x = cvt_pk_bf16(o2[0], o2[1]); w.y = cvt_pk_bf16(o2[2], o2[3]); *(u32x2*)(dst + sbj + 4 * n) = w; }
;                 }
;                 asm volatile("" ::: "memory");
.LBB0_683:
	s_or_b64 exec, exec, s[2:3]
	v_mul_f32_e32 v18, v6, v6
	v_mul_f32_e32 v19, v7, v7
	v_fmac_f32_e32 v18, v14, v14
	v_fmac_f32_e32 v19, v15, v15
	v_fmac_f32_e32 v18, v10, v10
	v_fmac_f32_e32 v19, v11, v11
	v_fmac_f32_e32 v18, v2, v2
	v_fmac_f32_e32 v19, v3, v3
	v_add_f32_e32 v18, v18, v19
	v_mul_f32_e32 v19, v8, v8
	v_fmac_f32_e32 v19, v16, v16
	v_fmac_f32_e32 v19, v12, v12
	v_fmac_f32_e32 v19, v4, v4
	v_add_f32_e32 v18, v19, v18
	v_mul_f32_e32 v19, v9, v9
	v_fmac_f32_e32 v19, v17, v17
	v_fmac_f32_e32 v19, v13, v13
	v_fmac_f32_e32 v19, v5, v5
	v_add_f32_e32 v18, v19, v18
	ds_swizzle_b32 v19, v18 offset:swizzle(SWAP,16)
	s_waitcnt lgkmcnt(0)
	v_add_f32_e32 v22, v18, v19
	v_mov_b32_e32 v23, v22
	s_nop 1
	v_permlane32_swap_b32_e32 v22, v23
	s_and_saveexec_b64 s[2:3], s[20:21]
	v_add_f32_e32 v22, v22, v23
	v_fmaak_f32 v22, v159, v22, 0x358637bd
	v_cmp_gt_f32_e64 s[42:43], s88, v22
	v_mul_f32_e32 v23, 0x4b800000, v22
	v_add_u32_e32 v18, 0xb0, v160
	v_cndmask_b32_e64 v22, v22, v23, s[42:43]
	v_rsq_f32_e32 v22, v22
	v_mad_u64_u32 v[18:19], s[20:21], s26, v18, v[142:143]
	v_mov_b32_e32 v19, v0
	v_mul_f32_e32 v23, 0x45800000, v22
	v_cndmask_b32_e64 v22, v22, v23, s[42:43]
	v_mul_f32_e32 v22, v143, v22
	v_cndmask_b32_e64 v22, v22, 1.0, s[50:51]
	v_pk_mul_f32 v[24:25], v[16:17], v[22:23] op_sel_hi:[1,0]
	v_pk_mul_f32 v[26:27], v[14:15], v[22:23] op_sel_hi:[1,0]
	v_pk_mul_f32 v[32:33], v[10:11], v[22:23] op_sel_hi:[1,0]
	v_pk_mul_f32 v[34:35], v[12:13], v[22:23] op_sel_hi:[1,0]
	v_lshl_add_u64 v[20:21], v[18:19], 1, s[60:61]
	s_lshl_b32 s54, s16, 1
	v_lshl_add_u64 v[18:19], v[20:21], 0, s[54:55]
	s_waitcnt vmcnt(9)
	v_pk_mul_f32 v[28:29], v[26:27], v[176:177]
	v_pk_mul_f32 v[30:31], v[24:25], v[178:179]
	s_waitcnt vmcnt(7)
	v_mov_b32_e32 v36, v184
	s_waitcnt vmcnt(6)
	v_pk_mul_f32 v[12:13], v[34:35], v[190:191]
	v_pk_mul_f32 v[10:11], v[32:33], v[188:189]
	v_mov_b32_e32 v32, v180
	v_mov_b32_e32 v33, v182
	v_mov_b32_e32 v37, v186
	v_mov_b32_e32 v186, v185
	v_mov_b32_e32 v182, v181
	v_pk_mul_f32 v[34:35], v[32:33], v[10:11]
	v_pk_mul_f32 v[38:39], v[36:37], v[12:13]
	v_pk_mul_f32 v[10:11], v[182:183], v[10:11]
	v_pk_mul_f32 v[12:13], v[186:187], v[12:13]
	v_pk_fma_f32 v[10:11], v[28:29], v[32:33], v[10:11] neg_lo:[0,0,1] neg_hi:[0,0,1]
	v_pk_fma_f32 v[12:13], v[30:31], v[36:37], v[12:13] neg_lo:[0,0,1] neg_hi:[0,0,1]
	v_pk_fma_f32 v[24:25], v[30:31], v[186:187], v[38:39]
	v_pk_fma_f32 v[14:15], v[28:29], v[182:183], v[34:35]
	v_cvt_pk_bf16_f32 v240, v10, v11
	v_cvt_pk_bf16_f32 v241, v12, v13
	v_cvt_pk_bf16_f32 v244, v14, v15
	v_cvt_pk_bf16_f32 v245, v24, v25
	v_pk_mul_f32 v[10:11], v[8:9], v[22:23] op_sel_hi:[1,0]
	v_pk_mul_f32 v[12:13], v[6:7], v[22:23] op_sel_hi:[1,0]
	v_pk_mul_f32 v[24:25], v[2:3], v[22:23] op_sel_hi:[1,0]
	s_waitcnt vmcnt(5)
	v_pk_mul_f32 v[14:15], v[12:13], v[192:193]
	v_pk_mul_f32 v[16:17], v[10:11], v[194:195]
	v_pk_mul_f32 v[22:23], v[4:5], v[22:23] op_sel_hi:[1,0]
	s_waitcnt vmcnt(3)
	v_mov_b32_e32 v26, v200
	v_mov_b32_e32 v27, v202
	s_waitcnt vmcnt(2)
	v_pk_mul_f32 v[4:5], v[22:23], v[206:207]
	v_pk_mul_f32 v[2:3], v[24:25], v[204:205]
	v_mov_b32_e32 v22, v196
	v_mov_b32_e32 v23, v198
	v_mov_b32_e32 v202, v201
	v_mov_b32_e32 v198, v197
	v_pk_mul_f32 v[24:25], v[22:23], v[2:3]
	v_pk_mul_f32 v[28:29], v[26:27], v[4:5]
	v_pk_mul_f32 v[2:3], v[198:199], v[2:3]
	v_pk_mul_f32 v[4:5], v[202:203], v[4:5]
	v_pk_fma_f32 v[2:3], v[14:15], v[22:23], v[2:3] neg_lo:[0,0,1] neg_hi:[0,0,1]
	v_pk_fma_f32 v[4:5], v[16:17], v[26:27], v[4:5] neg_lo:[0,0,1] neg_hi:[0,0,1]
	v_pk_fma_f32 v[10:11], v[16:17], v[202:203], v[28:29]
	v_pk_fma_f32 v[6:7], v[14:15], v[198:199], v[24:25]
	v_cvt_pk_bf16_f32 v242, v2, v3
	v_cvt_pk_bf16_f32 v243, v4, v5
	global_store_dwordx4 v[20:21], v[240:243], off
	v_cvt_pk_bf16_f32 v246, v6, v7
	v_cvt_pk_bf16_f32 v247, v10, v11
	global_store_dwordx4 v[18:19], v[244:247], off
	s_branch .LBB0_650
